# peel first GEMM loop iteration with inline-zero C operand, accumulator zeroing removed
# speedup vs baseline: 1.0247x; 1.0082x over previous
.LBB0_253:
	s_ashr_i32 s31, s30, 31
	v_cmp_lt_i64_e32 vcc, s[28:29], v[134:135]
	s_lshl_b64 s[28:29], s[30:31], 19
	v_readlane_b32 s36, v253, 45
	v_readlane_b32 s37, v253, 46
	s_add_u32 s36, s36, s28
	s_addc_u32 s37, s37, s29
	s_and_b64 s[28:29], vcc, exec
	s_cselect_b32 s31, s37, s21
	s_cselect_b32 s65, s36, s20
	s_ashr_i32 s1, s0, 31
	s_lshl_b64 s[28:29], s[0:1], 19
	v_readlane_b32 s42, v255, 0
	v_readlane_b32 s43, v255, 1
	s_add_u32 s42, s42, s28
	s_addc_u32 s43, s43, s29
	s_and_b64 s[28:29], vcc, exec
	s_cselect_b32 s1, s43, s3
	s_cselect_b32 s66, s42, s2
	s_add_u32 s20, s20, 0x40080
	s_addc_u32 s21, s21, 0
	s_add_u32 s67, s2, 0x100
	s_addc_u32 s68, s3, 0
	s_mov_b32 s69, -2
	s_waitcnt lgkmcnt(0)
	s_add_u32 s2, s20, 0xfffc0080
	s_addc_u32 s3, s21, -1
	s_add_i32 s70, 0, 0x10000
	v_add_u32_e32 v0, s70, v143
	ds_read_b128 v[156:159], v0
	ds_read_b128 v[170:173], v0 offset:1024
	ds_read_b128 v[174:177], v0 offset:2048
	ds_read_b128 v[178:181], v0 offset:3072
	s_cmp_eq_u32 s69, 12
	s_cselect_b32 s29, s31, s3
	s_cselect_b32 s28, s65, s2
	s_cselect_b32 s3, s1, s68
	s_cselect_b32 s2, s66, s67
	v_lshl_add_u64 v[130:131], s[20:21], 0, v[152:153]
	s_add_i32 m0, s33, 0xc000
	ds_read_b128 v[182:185], v169
	ds_read_b128 v[186:189], v169 offset:1024
	ds_read_b128 v[190:193], v169 offset:2048
	ds_read_b128 v[194:197], v169 offset:3072
	ds_read_b128 v[198:201], v169 offset:4096
	ds_read_b128 v[202:205], v169 offset:5120
	ds_read_b128 v[206:209], v169 offset:6144
	ds_read_b128 v[210:213], v169 offset:7168
	global_load_lds_dwordx4 v[130:131], off
	v_lshl_add_u64 v[130:131], s[20:21], 0, v[154:155]
	s_add_i32 m0, s33, 0xe000
	s_nop 0
	global_load_lds_dwordx4 v[130:131], off
	s_waitcnt lgkmcnt(8)
	s_barrier
	s_waitcnt lgkmcnt(0)
	v_mfma_f32_16x16x32_bf16 v[126:129], v[156:159], v[182:185], 0
	v_mfma_f32_16x16x32_bf16 v[122:125], v[174:177], v[182:185], 0
	v_mfma_f32_16x16x32_bf16 v[110:113], v[156:159], v[190:193], 0
	v_mfma_f32_16x16x32_bf16 v[106:109], v[174:177], v[190:193], 0
	v_mfma_f32_16x16x32_bf16 v[94:97], v[156:159], v[198:201], 0
	v_mfma_f32_16x16x32_bf16 v[90:93], v[174:177], v[198:201], 0
	v_mfma_f32_16x16x32_bf16 v[78:81], v[156:159], v[206:209], 0
	v_mfma_f32_16x16x32_bf16 v[74:77], v[174:177], v[206:209], 0
	v_mfma_f32_16x16x32_bf16 v[126:129], v[170:173], v[186:189], v[126:129]
	v_mfma_f32_16x16x32_bf16 v[122:125], v[178:181], v[186:189], v[122:125]
	v_mfma_f32_16x16x32_bf16 v[110:113], v[170:173], v[194:197], v[110:113]
	v_mfma_f32_16x16x32_bf16 v[106:109], v[178:181], v[194:197], v[106:109]
	v_mfma_f32_16x16x32_bf16 v[94:97], v[170:173], v[202:205], v[94:97]
	v_mfma_f32_16x16x32_bf16 v[90:93], v[178:181], v[202:205], v[90:93]
	v_mfma_f32_16x16x32_bf16 v[78:81], v[170:173], v[210:213], v[78:81]
	v_mfma_f32_16x16x32_bf16 v[74:77], v[178:181], v[210:213], v[74:77]
	s_barrier
	s_add_i32 s72, 0, 0x14000
	s_add_i32 s70, s70, s23
	v_add_u32_e32 v0, s72, v143
	v_lshl_add_u64 v[130:131], s[2:3], 0, v[148:149]
	s_mov_b32 m0, s70
	ds_read_b128 v[214:217], v0
	ds_read_b128 v[218:221], v0 offset:1024
	ds_read_b128 v[222:225], v0 offset:2048
	ds_read_b128 v[226:229], v0 offset:3072
	global_load_lds_dwordx4 v[130:131], off
	v_lshl_add_u64 v[132:133], s[2:3], 0, v[144:145]
	s_add_i32 m0, s70, 0x2000
	s_nop 0
	global_load_lds_dwordx4 v[132:133], off
	s_barrier
	s_waitcnt lgkmcnt(0)
	v_mfma_f32_16x16x32_bf16 v[118:121], v[214:217], v[182:185], 0
	v_mfma_f32_16x16x32_bf16 v[114:117], v[222:225], v[182:185], 0
	v_mfma_f32_16x16x32_bf16 v[102:105], v[214:217], v[190:193], 0
	v_mfma_f32_16x16x32_bf16 v[98:101], v[222:225], v[190:193], 0
	v_mfma_f32_16x16x32_bf16 v[86:89], v[214:217], v[198:201], 0
	v_mfma_f32_16x16x32_bf16 v[82:85], v[222:225], v[198:201], 0
	v_mfma_f32_16x16x32_bf16 v[70:73], v[214:217], v[206:209], 0
	v_mfma_f32_16x16x32_bf16 v[66:69], v[222:225], v[206:209], 0
	v_mfma_f32_16x16x32_bf16 v[118:121], v[218:221], v[186:189], v[118:121]
	v_mfma_f32_16x16x32_bf16 v[114:117], v[226:229], v[186:189], v[114:117]
	v_mfma_f32_16x16x32_bf16 v[102:105], v[218:221], v[194:197], v[102:105]
	v_mfma_f32_16x16x32_bf16 v[98:101], v[226:229], v[194:197], v[98:101]
	v_mfma_f32_16x16x32_bf16 v[86:89], v[218:221], v[202:205], v[86:89]
	v_mfma_f32_16x16x32_bf16 v[82:85], v[226:229], v[202:205], v[82:85]
	v_mfma_f32_16x16x32_bf16 v[70:73], v[218:221], v[210:213], v[70:73]
	v_mfma_f32_16x16x32_bf16 v[66:69], v[226:229], v[210:213], v[66:69]
	s_mov_b32 m0, s33
	v_lshl_add_u64 v[162:163], s[28:29], 0, v[150:151]
	s_barrier
	ds_read_b128 v[182:185], v169 offset:16384
	ds_read_b128 v[186:189], v169 offset:17408
	ds_read_b128 v[190:193], v169 offset:18432
	ds_read_b128 v[194:197], v169 offset:19456
	ds_read_b128 v[198:201], v169 offset:20480
	ds_read_b128 v[202:205], v169 offset:21504
	ds_read_b128 v[206:209], v169 offset:22528
	ds_read_b128 v[210:213], v169 offset:23552
	global_load_lds_dwordx4 v[162:163], off
	v_lshl_add_u64 v[164:165], s[28:29], 0, v[146:147]
	s_mov_b32 m0, s35
	s_nop 0
	global_load_lds_dwordx4 v[164:165], off
	s_barrier
	s_waitcnt lgkmcnt(0)
	v_mfma_f32_16x16x32_bf16 v[62:65], v[156:159], v[182:185], 0
	v_mfma_f32_16x16x32_bf16 v[58:61], v[174:177], v[182:185], 0
	v_mfma_f32_16x16x32_bf16 v[50:53], v[156:159], v[190:193], 0
	v_mfma_f32_16x16x32_bf16 v[42:45], v[174:177], v[190:193], 0
	v_mfma_f32_16x16x32_bf16 v[34:37], v[156:159], v[198:201], 0
	v_mfma_f32_16x16x32_bf16 v[26:29], v[174:177], v[198:201], 0
	v_mfma_f32_16x16x32_bf16 v[18:21], v[156:159], v[206:209], 0
	v_mfma_f32_16x16x32_bf16 v[10:13], v[174:177], v[206:209], 0
	v_mfma_f32_16x16x32_bf16 v[62:65], v[170:173], v[186:189], v[62:65]
	v_mfma_f32_16x16x32_bf16 v[58:61], v[178:181], v[186:189], v[58:61]
	v_mfma_f32_16x16x32_bf16 v[50:53], v[170:173], v[194:197], v[50:53]
	v_mfma_f32_16x16x32_bf16 v[42:45], v[178:181], v[194:197], v[42:45]
	v_mfma_f32_16x16x32_bf16 v[34:37], v[170:173], v[202:205], v[34:37]
	v_mfma_f32_16x16x32_bf16 v[26:29], v[178:181], v[202:205], v[26:29]
	v_mfma_f32_16x16x32_bf16 v[18:21], v[170:173], v[210:213], v[18:21]
	v_mfma_f32_16x16x32_bf16 v[10:13], v[178:181], v[210:213], v[10:13]
	s_barrier
	s_add_u32 s70, s2, 0x40000
	s_addc_u32 s71, s3, 0
	s_add_i32 s72, s72, s23
	v_lshl_add_u64 v[156:157], s[70:71], 0, v[148:149]
	s_mov_b32 m0, s72
	s_nop 0
	global_load_lds_dwordx4 v[156:157], off
	v_lshl_add_u64 v[156:157], s[70:71], 0, v[144:145]
	s_add_i32 m0, s72, 0x2000
	s_nop 0
	global_load_lds_dwordx4 v[156:157], off
	s_waitcnt vmcnt(6)
	s_barrier
	v_mfma_f32_16x16x32_bf16 v[54:57], v[214:217], v[182:185], 0
	v_mfma_f32_16x16x32_bf16 v[46:49], v[222:225], v[182:185], 0
	v_mfma_f32_16x16x32_bf16 v[38:41], v[214:217], v[190:193], 0
	v_mfma_f32_16x16x32_bf16 v[30:33], v[222:225], v[190:193], 0
	v_mfma_f32_16x16x32_bf16 v[22:25], v[214:217], v[198:201], 0
	v_mfma_f32_16x16x32_bf16 v[14:17], v[222:225], v[198:201], 0
	v_mfma_f32_16x16x32_bf16 v[6:9], v[214:217], v[206:209], 0
	v_mfma_f32_16x16x32_bf16 v[2:5], v[222:225], v[206:209], 0
	v_mfma_f32_16x16x32_bf16 v[54:57], v[218:221], v[186:189], v[54:57]
	v_mfma_f32_16x16x32_bf16 v[46:49], v[226:229], v[186:189], v[46:49]
	v_mfma_f32_16x16x32_bf16 v[38:41], v[218:221], v[194:197], v[38:41]
	v_mfma_f32_16x16x32_bf16 v[30:33], v[226:229], v[194:197], v[30:33]
	v_mfma_f32_16x16x32_bf16 v[22:25], v[218:221], v[202:205], v[22:25]
	v_mfma_f32_16x16x32_bf16 v[14:17], v[226:229], v[202:205], v[14:17]
	v_mfma_f32_16x16x32_bf16 v[6:9], v[218:221], v[210:213], v[6:9]
	v_mfma_f32_16x16x32_bf16 v[2:5], v[226:229], v[210:213], v[2:5]
	s_add_i32 s70, 0, 0x18000
	v_add_u32_e32 v0, s70, v143
	s_barrier
	ds_read_b128 v[156:159], v0
	ds_read_b128 v[170:173], v0 offset:1024
	ds_read_b128 v[174:177], v0 offset:2048
	ds_read_b128 v[178:181], v0 offset:3072
	s_add_u32 s28, s28, 0x40000
	s_addc_u32 s29, s29, 0
	s_mov_b32 m0, s41
	v_lshl_add_u64 v[214:215], s[28:29], 0, v[150:151]
	ds_read_b128 v[182:185], v169 offset:32768
	ds_read_b128 v[186:189], v169 offset:33792
	ds_read_b128 v[190:193], v169 offset:34816
	ds_read_b128 v[194:197], v169 offset:35840
	ds_read_b128 v[198:201], v169 offset:36864
	ds_read_b128 v[202:205], v169 offset:37888
	ds_read_b128 v[206:209], v169 offset:38912
	ds_read_b128 v[210:213], v169 offset:39936
	global_load_lds_dwordx4 v[214:215], off
	v_lshl_add_u64 v[214:215], s[28:29], 0, v[146:147]
	s_mov_b32 m0, s44
	s_nop 0
	global_load_lds_dwordx4 v[214:215], off
	s_waitcnt lgkmcnt(8)
	s_barrier
	s_waitcnt lgkmcnt(0)
	v_mfma_f32_16x16x32_bf16 v[126:129], v[156:159], v[182:185], v[126:129]
	v_mfma_f32_16x16x32_bf16 v[122:125], v[174:177], v[182:185], v[122:125]
	v_mfma_f32_16x16x32_bf16 v[110:113], v[156:159], v[190:193], v[110:113]
	v_mfma_f32_16x16x32_bf16 v[106:109], v[174:177], v[190:193], v[106:109]
	v_mfma_f32_16x16x32_bf16 v[94:97], v[156:159], v[198:201], v[94:97]
	v_mfma_f32_16x16x32_bf16 v[90:93], v[174:177], v[198:201], v[90:93]
	v_mfma_f32_16x16x32_bf16 v[78:81], v[156:159], v[206:209], v[78:81]
	v_mfma_f32_16x16x32_bf16 v[74:77], v[174:177], v[206:209], v[74:77]
	v_mfma_f32_16x16x32_bf16 v[126:129], v[170:173], v[186:189], v[126:129]
	v_mfma_f32_16x16x32_bf16 v[122:125], v[178:181], v[186:189], v[122:125]
	v_mfma_f32_16x16x32_bf16 v[110:113], v[170:173], v[194:197], v[110:113]
	v_mfma_f32_16x16x32_bf16 v[106:109], v[178:181], v[194:197], v[106:109]
	v_mfma_f32_16x16x32_bf16 v[94:97], v[170:173], v[202:205], v[94:97]
	v_mfma_f32_16x16x32_bf16 v[90:93], v[178:181], v[202:205], v[90:93]
	v_mfma_f32_16x16x32_bf16 v[78:81], v[170:173], v[210:213], v[78:81]
	v_mfma_f32_16x16x32_bf16 v[74:77], v[178:181], v[210:213], v[74:77]
	s_barrier
	s_add_i32 s28, 0, 0x1c000
	s_add_i32 s29, s70, s23
	v_add_u32_e32 v0, s28, v143
	v_lshl_add_u64 v[130:131], v[130:131], 0, s[26:27]
	s_mov_b32 m0, s29
	ds_read_b128 v[214:217], v0
	ds_read_b128 v[218:221], v0 offset:1024
	ds_read_b128 v[222:225], v0 offset:2048
	ds_read_b128 v[226:229], v0 offset:3072
	global_load_lds_dwordx4 v[130:131], off
	v_lshl_add_u64 v[130:131], v[132:133], 0, s[26:27]
	s_add_i32 m0, s29, 0x2000
	s_nop 0
	global_load_lds_dwordx4 v[130:131], off
	s_barrier
	s_waitcnt lgkmcnt(0)
	v_mfma_f32_16x16x32_bf16 v[118:121], v[214:217], v[182:185], v[118:121]
	v_mfma_f32_16x16x32_bf16 v[114:117], v[222:225], v[182:185], v[114:117]
	v_mfma_f32_16x16x32_bf16 v[102:105], v[214:217], v[190:193], v[102:105]
	v_mfma_f32_16x16x32_bf16 v[98:101], v[222:225], v[190:193], v[98:101]
	v_mfma_f32_16x16x32_bf16 v[86:89], v[214:217], v[198:201], v[86:89]
	v_mfma_f32_16x16x32_bf16 v[82:85], v[222:225], v[198:201], v[82:85]
	v_mfma_f32_16x16x32_bf16 v[70:73], v[214:217], v[206:209], v[70:73]
	v_mfma_f32_16x16x32_bf16 v[66:69], v[222:225], v[206:209], v[66:69]
	v_mfma_f32_16x16x32_bf16 v[118:121], v[218:221], v[186:189], v[118:121]
	v_mfma_f32_16x16x32_bf16 v[114:117], v[226:229], v[186:189], v[114:117]
	v_mfma_f32_16x16x32_bf16 v[102:105], v[218:221], v[194:197], v[102:105]
	v_mfma_f32_16x16x32_bf16 v[98:101], v[226:229], v[194:197], v[98:101]
	v_mfma_f32_16x16x32_bf16 v[86:89], v[218:221], v[202:205], v[86:89]
	v_mfma_f32_16x16x32_bf16 v[82:85], v[226:229], v[202:205], v[82:85]
	v_mfma_f32_16x16x32_bf16 v[70:73], v[218:221], v[210:213], v[70:73]
	v_mfma_f32_16x16x32_bf16 v[66:69], v[226:229], v[210:213], v[66:69]
	s_mov_b32 m0, s40
	v_lshl_add_u64 v[130:131], v[162:163], 0, s[26:27]
	s_barrier
	ds_read_b128 v[182:185], v169 offset:49152
	ds_read_b128 v[186:189], v169 offset:50176
	ds_read_b128 v[190:193], v169 offset:51200
	ds_read_b128 v[194:197], v169 offset:52224
	ds_read_b128 v[198:201], v169 offset:53248
	ds_read_b128 v[202:205], v169 offset:54272
	ds_read_b128 v[206:209], v169 offset:55296
	ds_read_b128 v[210:213], v169 offset:56320
	global_load_lds_dwordx4 v[130:131], off
	v_lshl_add_u64 v[130:131], v[164:165], 0, s[26:27]
	s_mov_b32 m0, s45
	s_nop 0
	global_load_lds_dwordx4 v[130:131], off
	s_barrier
	s_waitcnt lgkmcnt(0)
	v_mfma_f32_16x16x32_bf16 v[62:65], v[156:159], v[182:185], v[62:65]
	v_mfma_f32_16x16x32_bf16 v[58:61], v[174:177], v[182:185], v[58:61]
	v_mfma_f32_16x16x32_bf16 v[50:53], v[156:159], v[190:193], v[50:53]
	v_mfma_f32_16x16x32_bf16 v[42:45], v[174:177], v[190:193], v[42:45]
	v_mfma_f32_16x16x32_bf16 v[34:37], v[156:159], v[198:201], v[34:37]
	v_mfma_f32_16x16x32_bf16 v[26:29], v[174:177], v[198:201], v[26:29]
	v_mfma_f32_16x16x32_bf16 v[18:21], v[156:159], v[206:209], v[18:21]
	v_mfma_f32_16x16x32_bf16 v[10:13], v[174:177], v[206:209], v[10:13]
	v_mfma_f32_16x16x32_bf16 v[62:65], v[170:173], v[186:189], v[62:65]
	v_mfma_f32_16x16x32_bf16 v[58:61], v[178:181], v[186:189], v[58:61]
	v_mfma_f32_16x16x32_bf16 v[50:53], v[170:173], v[194:197], v[50:53]
	v_mfma_f32_16x16x32_bf16 v[42:45], v[178:181], v[194:197], v[42:45]
	v_mfma_f32_16x16x32_bf16 v[34:37], v[170:173], v[202:205], v[34:37]
	v_mfma_f32_16x16x32_bf16 v[26:29], v[178:181], v[202:205], v[26:29]
	v_mfma_f32_16x16x32_bf16 v[18:21], v[170:173], v[210:213], v[18:21]
	v_mfma_f32_16x16x32_bf16 v[10:13], v[178:181], v[210:213], v[10:13]
	s_barrier
	s_add_u32 s2, s2, 0x40080
	s_addc_u32 s3, s3, 0
	s_add_i32 s28, s28, s23
	v_lshl_add_u64 v[130:131], s[2:3], 0, v[148:149]
	s_mov_b32 m0, s28
	s_nop 0
	global_load_lds_dwordx4 v[130:131], off
	v_lshl_add_u64 v[130:131], s[2:3], 0, v[144:145]
	s_add_i32 m0, s28, 0x2000
	s_nop 0
	global_load_lds_dwordx4 v[130:131], off
	s_waitcnt vmcnt(6)
	s_barrier
	v_mfma_f32_16x16x32_bf16 v[54:57], v[214:217], v[182:185], v[54:57]
	v_mfma_f32_16x16x32_bf16 v[46:49], v[222:225], v[182:185], v[46:49]
	v_mfma_f32_16x16x32_bf16 v[38:41], v[214:217], v[190:193], v[38:41]
	v_mfma_f32_16x16x32_bf16 v[30:33], v[222:225], v[190:193], v[30:33]
	v_mfma_f32_16x16x32_bf16 v[22:25], v[214:217], v[198:201], v[22:25]
	v_mfma_f32_16x16x32_bf16 v[14:17], v[222:225], v[198:201], v[14:17]
	v_mfma_f32_16x16x32_bf16 v[6:9], v[214:217], v[206:209], v[6:9]
	v_mfma_f32_16x16x32_bf16 v[2:5], v[222:225], v[206:209], v[2:5]
	v_mfma_f32_16x16x32_bf16 v[54:57], v[218:221], v[186:189], v[54:57]
	v_mfma_f32_16x16x32_bf16 v[46:49], v[226:229], v[186:189], v[46:49]
	v_mfma_f32_16x16x32_bf16 v[38:41], v[218:221], v[194:197], v[38:41]
	v_mfma_f32_16x16x32_bf16 v[30:33], v[226:229], v[194:197], v[30:33]
	v_mfma_f32_16x16x32_bf16 v[22:25], v[218:221], v[202:205], v[22:25]
	v_mfma_f32_16x16x32_bf16 v[14:17], v[226:229], v[202:205], v[14:17]
	v_mfma_f32_16x16x32_bf16 v[6:9], v[218:221], v[210:213], v[6:9]
	v_mfma_f32_16x16x32_bf16 v[2:5], v[226:229], v[210:213], v[2:5]
	s_add_i32 s69, s69, 2
	s_add_u32 s20, s20, 0x100
	s_addc_u32 s21, s21, 0
	s_add_u32 s67, s67, 0x100
	s_addc_u32 s68, s68, 0
	s_cmp_gt_u32 s69, 13
	s_barrier
	s_cbranch_scc0 .LBB0_254
	s_branch .Lafter_254

.Lafter_254:
	s_add_i32 s1, s47, -4
	v_readlane_b32 s20, v251, 20
	v_lshl_add_u32 v156, s64, 8, v141
	s_cmp_gt_u32 s1, 7
	s_mov_b64 s[2:3], -1
	v_readlane_b32 s21, v251, 21
	s_cbranch_scc0 .LBB0_261
	s_mov_b64 s[2:3], 0
	s_cmp_lt_i32 s47, 4
	s_mov_b32 s1, s47
	s_cbranch_scc1 .LBB0_260
	s_add_i32 s1, s47, -12
	s_cmp_lt_u32 s1, 4
	s_mov_b64 s[2:3], 0x30c0000
	s_cbranch_scc1 .LBB0_259
	s_lshr_b32 s1, s1, 2
	s_add_i32 s2, s1, 2
	s_cmp_lg_u32 s1, 1
	s_cselect_b32 s1, s2, 1
	s_mul_hi_u32 s3, s1, 0x1040000
	s_mul_i32 s2, s1, 0x1040000

.LBB0_317:
	s_add_i32 s22, s68, -2
	s_add_u32 vcc_lo, s2, 0x80
	s_addc_u32 vcc_hi, s3, 0
	s_add_u32 s23, s98, 0x100
	s_addc_u32 s47, s99, 0
	s_mov_b32 s2, 0
	s_waitcnt lgkmcnt(0)
	s_add_i32 s71, s2, 2
	s_add_u32 s98, vcc_lo, 0x80
	s_addc_u32 s3, vcc_hi, 0
	s_add_i32 s73, 0, 0x10000
	v_add_u32_e32 v0, s73, v143
	ds_read_b128 v[168:171], v0
	ds_read_b128 v[172:175], v0 offset:1024
	ds_read_b128 v[176:179], v0 offset:2048
	ds_read_b128 v[180:183], v0 offset:3072
	s_cmp_eq_u32 s22, s2
	s_cselect_b32 s2, s20, s98
	s_cselect_b32 s3, s21, s3
	s_cselect_b32 s99, s1, s47
	s_cselect_b32 s98, s0, s23
	v_lshl_add_u64 v[130:131], vcc, 0, v[152:153]
	s_add_i32 m0, s43, 0xc000
	ds_read_b128 v[184:187], v159
	ds_read_b128 v[188:191], v159 offset:1024
	ds_read_b128 v[192:195], v159 offset:2048
	ds_read_b128 v[196:199], v159 offset:3072
	ds_read_b128 v[200:203], v159 offset:4096
	ds_read_b128 v[204:207], v159 offset:5120
	ds_read_b128 v[208:211], v159 offset:6144
	ds_read_b128 v[212:215], v159 offset:7168
	global_load_lds_dwordx4 v[130:131], off
	v_lshl_add_u64 v[130:131], vcc, 0, v[154:155]
	s_add_i32 m0, s43, 0xe000
	s_nop 0
	global_load_lds_dwordx4 v[130:131], off
	s_waitcnt lgkmcnt(8)
	s_barrier
	s_waitcnt lgkmcnt(0)
	v_mfma_f32_16x16x32_bf16 v[126:129], v[168:171], v[184:187], 0
	v_mfma_f32_16x16x32_bf16 v[122:125], v[176:179], v[184:187], 0
	v_mfma_f32_16x16x32_bf16 v[118:121], v[168:171], v[192:195], 0
	v_mfma_f32_16x16x32_bf16 v[110:113], v[176:179], v[192:195], 0
	v_mfma_f32_16x16x32_bf16 v[102:105], v[168:171], v[200:203], 0
	v_mfma_f32_16x16x32_bf16 v[94:97], v[176:179], v[200:203], 0
	v_mfma_f32_16x16x32_bf16 v[86:89], v[168:171], v[208:211], 0
	v_mfma_f32_16x16x32_bf16 v[78:81], v[176:179], v[208:211], 0
	v_mfma_f32_16x16x32_bf16 v[126:129], v[172:175], v[188:191], v[126:129]
	v_mfma_f32_16x16x32_bf16 v[122:125], v[180:183], v[188:191], v[122:125]
	v_mfma_f32_16x16x32_bf16 v[118:121], v[172:175], v[196:199], v[118:121]
	v_mfma_f32_16x16x32_bf16 v[110:113], v[180:183], v[196:199], v[110:113]
	v_mfma_f32_16x16x32_bf16 v[102:105], v[172:175], v[204:207], v[102:105]
	v_mfma_f32_16x16x32_bf16 v[94:97], v[180:183], v[204:207], v[94:97]
	v_mfma_f32_16x16x32_bf16 v[86:89], v[172:175], v[212:215], v[86:89]
	v_mfma_f32_16x16x32_bf16 v[78:81], v[180:183], v[212:215], v[78:81]
	s_barrier
	s_add_i32 s70, 0, 0x14000
	s_add_i32 s73, s73, s41
	v_add_u32_e32 v0, s70, v143
	v_lshl_add_u64 v[130:131], s[98:99], 0, v[146:147]
	s_mov_b32 m0, s73
	ds_read_b128 v[216:219], v0
	ds_read_b128 v[220:223], v0 offset:1024
	ds_read_b128 v[224:227], v0 offset:2048
	ds_read_b128 v[228:231], v0 offset:3072
	global_load_lds_dwordx4 v[130:131], off
	v_lshl_add_u64 v[132:133], s[98:99], 0, v[150:151]
	s_add_i32 m0, s73, 0x2000
	s_nop 0
	global_load_lds_dwordx4 v[132:133], off
	s_barrier
	s_waitcnt lgkmcnt(0)
	v_mfma_f32_16x16x32_bf16 v[114:117], v[216:219], v[184:187], 0
	v_mfma_f32_16x16x32_bf16 v[106:109], v[224:227], v[184:187], 0
	v_mfma_f32_16x16x32_bf16 v[98:101], v[216:219], v[192:195], 0
	v_mfma_f32_16x16x32_bf16 v[90:93], v[224:227], v[192:195], 0
	v_mfma_f32_16x16x32_bf16 v[82:85], v[216:219], v[200:203], 0
	v_mfma_f32_16x16x32_bf16 v[74:77], v[224:227], v[200:203], 0
	v_mfma_f32_16x16x32_bf16 v[70:73], v[216:219], v[208:211], 0
	v_mfma_f32_16x16x32_bf16 v[66:69], v[224:227], v[208:211], 0
	v_mfma_f32_16x16x32_bf16 v[114:117], v[220:223], v[188:191], v[114:117]
	v_mfma_f32_16x16x32_bf16 v[106:109], v[228:231], v[188:191], v[106:109]
	v_mfma_f32_16x16x32_bf16 v[98:101], v[220:223], v[196:199], v[98:101]
	v_mfma_f32_16x16x32_bf16 v[90:93], v[228:231], v[196:199], v[90:93]
	v_mfma_f32_16x16x32_bf16 v[82:85], v[220:223], v[204:207], v[82:85]
	v_mfma_f32_16x16x32_bf16 v[74:77], v[228:231], v[204:207], v[74:77]
	v_mfma_f32_16x16x32_bf16 v[70:73], v[220:223], v[212:215], v[70:73]
	v_mfma_f32_16x16x32_bf16 v[66:69], v[228:231], v[212:215], v[66:69]
	s_mov_b32 m0, s43
	v_lshl_add_u64 v[156:157], s[2:3], 0, v[144:145]
	s_barrier
	ds_read_b128 v[184:187], v159 offset:16384
	ds_read_b128 v[188:191], v159 offset:17408
	ds_read_b128 v[192:195], v159 offset:18432
	ds_read_b128 v[196:199], v159 offset:19456
	ds_read_b128 v[200:203], v159 offset:20480
	ds_read_b128 v[204:207], v159 offset:21504
	ds_read_b128 v[208:211], v159 offset:22528
	ds_read_b128 v[212:215], v159 offset:23552
	global_load_lds_dwordx4 v[156:157], off
	v_lshl_add_u64 v[162:163], s[2:3], 0, v[148:149]
	s_mov_b32 m0, s44
	s_nop 0
	global_load_lds_dwordx4 v[162:163], off
	s_barrier
	s_waitcnt lgkmcnt(0)
	v_mfma_f32_16x16x32_bf16 v[62:65], v[168:171], v[184:187], 0
	v_mfma_f32_16x16x32_bf16 v[58:61], v[176:179], v[184:187], 0
	v_mfma_f32_16x16x32_bf16 v[54:57], v[168:171], v[192:195], 0
	v_mfma_f32_16x16x32_bf16 v[46:49], v[176:179], v[192:195], 0
	v_mfma_f32_16x16x32_bf16 v[38:41], v[168:171], v[200:203], 0
	v_mfma_f32_16x16x32_bf16 v[30:33], v[176:179], v[200:203], 0
	v_mfma_f32_16x16x32_bf16 v[22:25], v[168:171], v[208:211], 0
	v_mfma_f32_16x16x32_bf16 v[14:17], v[176:179], v[208:211], 0
	v_mfma_f32_16x16x32_bf16 v[62:65], v[172:175], v[188:191], v[62:65]
	v_mfma_f32_16x16x32_bf16 v[58:61], v[180:183], v[188:191], v[58:61]
	v_mfma_f32_16x16x32_bf16 v[54:57], v[172:175], v[196:199], v[54:57]
	v_mfma_f32_16x16x32_bf16 v[46:49], v[180:183], v[196:199], v[46:49]
	v_mfma_f32_16x16x32_bf16 v[38:41], v[172:175], v[204:207], v[38:41]
	v_mfma_f32_16x16x32_bf16 v[30:33], v[180:183], v[204:207], v[30:33]
	v_mfma_f32_16x16x32_bf16 v[22:25], v[172:175], v[212:215], v[22:25]
	v_mfma_f32_16x16x32_bf16 v[14:17], v[180:183], v[212:215], v[14:17]
	s_barrier
	s_add_u32 s98, s98, s96
	s_addc_u32 s99, s99, 0
	s_add_i32 s70, s70, s41
	v_lshl_add_u64 v[164:165], s[98:99], 0, v[146:147]
	s_mov_b32 m0, s70
	v_lshl_add_u64 v[232:233], s[98:99], 0, v[150:151]
	global_load_lds_dwordx4 v[164:165], off
	s_add_i32 m0, s70, 0x2000
	s_nop 0
	global_load_lds_dwordx4 v[232:233], off
	s_waitcnt vmcnt(6)
	s_barrier
	v_mfma_f32_16x16x32_bf16 v[50:53], v[216:219], v[184:187], 0
	v_mfma_f32_16x16x32_bf16 v[42:45], v[224:227], v[184:187], 0
	v_mfma_f32_16x16x32_bf16 v[34:37], v[216:219], v[192:195], 0
	v_mfma_f32_16x16x32_bf16 v[26:29], v[224:227], v[192:195], 0
	v_mfma_f32_16x16x32_bf16 v[18:21], v[216:219], v[200:203], 0
	v_mfma_f32_16x16x32_bf16 v[10:13], v[224:227], v[200:203], 0
	v_mfma_f32_16x16x32_bf16 v[6:9], v[216:219], v[208:211], 0
	v_mfma_f32_16x16x32_bf16 v[2:5], v[224:227], v[208:211], 0
	v_mfma_f32_16x16x32_bf16 v[50:53], v[220:223], v[188:191], v[50:53]
	v_mfma_f32_16x16x32_bf16 v[42:45], v[228:231], v[188:191], v[42:45]
	v_mfma_f32_16x16x32_bf16 v[34:37], v[220:223], v[196:199], v[34:37]
	v_mfma_f32_16x16x32_bf16 v[26:29], v[228:231], v[196:199], v[26:29]
	v_mfma_f32_16x16x32_bf16 v[18:21], v[220:223], v[204:207], v[18:21]
	v_mfma_f32_16x16x32_bf16 v[10:13], v[228:231], v[204:207], v[10:13]
	v_mfma_f32_16x16x32_bf16 v[6:9], v[220:223], v[212:215], v[6:9]
	v_mfma_f32_16x16x32_bf16 v[2:5], v[228:231], v[212:215], v[2:5]
	s_add_i32 s70, 0, 0x18000
	v_add_u32_e32 v0, s70, v143
	s_barrier
	ds_read_b128 v[168:171], v0
	ds_read_b128 v[172:175], v0 offset:1024
	ds_read_b128 v[176:179], v0 offset:2048
	ds_read_b128 v[180:183], v0 offset:3072
	s_add_u32 s2, s2, s96
	s_addc_u32 s3, s3, 0
	s_mov_b32 m0, s45
	v_lshl_add_u64 v[216:217], s[2:3], 0, v[144:145]
	ds_read_b128 v[184:187], v159 offset:32768
	ds_read_b128 v[188:191], v159 offset:33792
	ds_read_b128 v[192:195], v159 offset:34816
	ds_read_b128 v[196:199], v159 offset:35840
	ds_read_b128 v[200:203], v159 offset:36864
	ds_read_b128 v[204:207], v159 offset:37888
	ds_read_b128 v[208:211], v159 offset:38912
	ds_read_b128 v[212:215], v159 offset:39936
	global_load_lds_dwordx4 v[216:217], off
	v_lshl_add_u64 v[216:217], s[2:3], 0, v[148:149]
	s_mov_b32 m0, s40
	s_nop 0
	global_load_lds_dwordx4 v[216:217], off
	s_waitcnt lgkmcnt(8)
	s_barrier
	s_waitcnt lgkmcnt(0)
	v_mfma_f32_16x16x32_bf16 v[126:129], v[168:171], v[184:187], v[126:129]
	v_mfma_f32_16x16x32_bf16 v[122:125], v[176:179], v[184:187], v[122:125]
	v_mfma_f32_16x16x32_bf16 v[118:121], v[168:171], v[192:195], v[118:121]
	v_mfma_f32_16x16x32_bf16 v[110:113], v[176:179], v[192:195], v[110:113]
	v_mfma_f32_16x16x32_bf16 v[102:105], v[168:171], v[200:203], v[102:105]
	v_mfma_f32_16x16x32_bf16 v[94:97], v[176:179], v[200:203], v[94:97]
	v_mfma_f32_16x16x32_bf16 v[86:89], v[168:171], v[208:211], v[86:89]
	v_mfma_f32_16x16x32_bf16 v[78:81], v[176:179], v[208:211], v[78:81]
	v_mfma_f32_16x16x32_bf16 v[126:129], v[172:175], v[188:191], v[126:129]
	v_mfma_f32_16x16x32_bf16 v[122:125], v[180:183], v[188:191], v[122:125]
	v_mfma_f32_16x16x32_bf16 v[118:121], v[172:175], v[196:199], v[118:121]
	v_mfma_f32_16x16x32_bf16 v[110:113], v[180:183], v[196:199], v[110:113]
	v_mfma_f32_16x16x32_bf16 v[102:105], v[172:175], v[204:207], v[102:105]
	v_mfma_f32_16x16x32_bf16 v[94:97], v[180:183], v[204:207], v[94:97]
	v_mfma_f32_16x16x32_bf16 v[86:89], v[172:175], v[212:215], v[86:89]
	v_mfma_f32_16x16x32_bf16 v[78:81], v[180:183], v[212:215], v[78:81]
	s_barrier
	s_add_i32 s2, 0, 0x1c000
	s_add_i32 s3, s70, s41
	v_add_u32_e32 v0, s2, v143
	v_lshl_add_u64 v[130:131], v[130:131], 0, s[26:27]
	s_mov_b32 m0, s3
	ds_read_b128 v[216:219], v0
	ds_read_b128 v[220:223], v0 offset:1024
	ds_read_b128 v[224:227], v0 offset:2048
	ds_read_b128 v[228:231], v0 offset:3072
	global_load_lds_dwordx4 v[130:131], off
	v_lshl_add_u64 v[130:131], v[132:133], 0, s[26:27]
	s_add_i32 m0, s3, 0x2000
	s_nop 0
	global_load_lds_dwordx4 v[130:131], off
	s_barrier
	s_waitcnt lgkmcnt(0)
	v_mfma_f32_16x16x32_bf16 v[114:117], v[216:219], v[184:187], v[114:117]
	v_mfma_f32_16x16x32_bf16 v[106:109], v[224:227], v[184:187], v[106:109]
	v_mfma_f32_16x16x32_bf16 v[98:101], v[216:219], v[192:195], v[98:101]
	v_mfma_f32_16x16x32_bf16 v[90:93], v[224:227], v[192:195], v[90:93]
	v_mfma_f32_16x16x32_bf16 v[82:85], v[216:219], v[200:203], v[82:85]
	v_mfma_f32_16x16x32_bf16 v[74:77], v[224:227], v[200:203], v[74:77]
	v_mfma_f32_16x16x32_bf16 v[70:73], v[216:219], v[208:211], v[70:73]
	v_mfma_f32_16x16x32_bf16 v[66:69], v[224:227], v[208:211], v[66:69]
	v_mfma_f32_16x16x32_bf16 v[114:117], v[220:223], v[188:191], v[114:117]
	v_mfma_f32_16x16x32_bf16 v[106:109], v[228:231], v[188:191], v[106:109]
	v_mfma_f32_16x16x32_bf16 v[98:101], v[220:223], v[196:199], v[98:101]
	v_mfma_f32_16x16x32_bf16 v[90:93], v[228:231], v[196:199], v[90:93]
	v_mfma_f32_16x16x32_bf16 v[82:85], v[220:223], v[204:207], v[82:85]
	v_mfma_f32_16x16x32_bf16 v[74:77], v[228:231], v[204:207], v[74:77]
	v_mfma_f32_16x16x32_bf16 v[70:73], v[220:223], v[212:215], v[70:73]
	v_mfma_f32_16x16x32_bf16 v[66:69], v[228:231], v[212:215], v[66:69]
	s_mov_b32 m0, s66
	v_lshl_add_u64 v[130:131], v[156:157], 0, s[26:27]
	s_barrier
	ds_read_b128 v[184:187], v159 offset:49152
	ds_read_b128 v[188:191], v159 offset:50176
	ds_read_b128 v[192:195], v159 offset:51200
	ds_read_b128 v[196:199], v159 offset:52224
	ds_read_b128 v[200:203], v159 offset:53248
	ds_read_b128 v[204:207], v159 offset:54272
	ds_read_b128 v[208:211], v159 offset:55296
	ds_read_b128 v[212:215], v159 offset:56320
	global_load_lds_dwordx4 v[130:131], off
	v_lshl_add_u64 v[130:131], v[162:163], 0, s[26:27]
	s_mov_b32 m0, s67
	s_nop 0
	global_load_lds_dwordx4 v[130:131], off
	s_barrier
	s_waitcnt lgkmcnt(0)
	v_mfma_f32_16x16x32_bf16 v[62:65], v[168:171], v[184:187], v[62:65]
	v_mfma_f32_16x16x32_bf16 v[58:61], v[176:179], v[184:187], v[58:61]
	v_mfma_f32_16x16x32_bf16 v[54:57], v[168:171], v[192:195], v[54:57]
	v_mfma_f32_16x16x32_bf16 v[46:49], v[176:179], v[192:195], v[46:49]
	v_mfma_f32_16x16x32_bf16 v[38:41], v[168:171], v[200:203], v[38:41]
	v_mfma_f32_16x16x32_bf16 v[30:33], v[176:179], v[200:203], v[30:33]
	v_mfma_f32_16x16x32_bf16 v[22:25], v[168:171], v[208:211], v[22:25]
	v_mfma_f32_16x16x32_bf16 v[14:17], v[176:179], v[208:211], v[14:17]
	v_mfma_f32_16x16x32_bf16 v[62:65], v[172:175], v[188:191], v[62:65]
	v_mfma_f32_16x16x32_bf16 v[58:61], v[180:183], v[188:191], v[58:61]
	v_mfma_f32_16x16x32_bf16 v[54:57], v[172:175], v[196:199], v[54:57]
	v_mfma_f32_16x16x32_bf16 v[46:49], v[180:183], v[196:199], v[46:49]
	v_mfma_f32_16x16x32_bf16 v[38:41], v[172:175], v[204:207], v[38:41]
	v_mfma_f32_16x16x32_bf16 v[30:33], v[180:183], v[204:207], v[30:33]
	v_mfma_f32_16x16x32_bf16 v[22:25], v[172:175], v[212:215], v[22:25]
	v_mfma_f32_16x16x32_bf16 v[14:17], v[180:183], v[212:215], v[14:17]
	s_barrier
	s_add_i32 s2, s2, s41
	v_lshl_add_u64 v[130:131], v[164:165], 0, s[26:27]
	s_mov_b32 m0, s2
	s_nop 0
	global_load_lds_dwordx4 v[130:131], off
	v_lshl_add_u64 v[130:131], v[232:233], 0, s[26:27]
	s_add_i32 m0, s2, 0x2000
	s_nop 0
	global_load_lds_dwordx4 v[130:131], off
	s_waitcnt vmcnt(6)
	s_barrier
	v_mfma_f32_16x16x32_bf16 v[50:53], v[216:219], v[184:187], v[50:53]
	v_mfma_f32_16x16x32_bf16 v[42:45], v[224:227], v[184:187], v[42:45]
	v_mfma_f32_16x16x32_bf16 v[34:37], v[216:219], v[192:195], v[34:37]
	v_mfma_f32_16x16x32_bf16 v[26:29], v[224:227], v[192:195], v[26:29]
	v_mfma_f32_16x16x32_bf16 v[18:21], v[216:219], v[200:203], v[18:21]
	v_mfma_f32_16x16x32_bf16 v[10:13], v[224:227], v[200:203], v[10:13]
	v_mfma_f32_16x16x32_bf16 v[6:9], v[216:219], v[208:211], v[6:9]
	v_mfma_f32_16x16x32_bf16 v[2:5], v[224:227], v[208:211], v[2:5]
	v_mfma_f32_16x16x32_bf16 v[50:53], v[220:223], v[188:191], v[50:53]
	v_mfma_f32_16x16x32_bf16 v[42:45], v[228:231], v[188:191], v[42:45]
	v_mfma_f32_16x16x32_bf16 v[34:37], v[220:223], v[196:199], v[34:37]
	v_mfma_f32_16x16x32_bf16 v[26:29], v[228:231], v[196:199], v[26:29]
	v_mfma_f32_16x16x32_bf16 v[18:21], v[220:223], v[204:207], v[18:21]
	v_mfma_f32_16x16x32_bf16 v[10:13], v[228:231], v[204:207], v[10:13]
	v_mfma_f32_16x16x32_bf16 v[6:9], v[220:223], v[212:215], v[6:9]
	v_mfma_f32_16x16x32_bf16 v[2:5], v[228:231], v[212:215], v[2:5]
	s_add_u32 vcc_lo, vcc_lo, 0x100
	s_addc_u32 vcc_hi, vcc_hi, 0
	s_add_u32 s23, s23, 0x100
	s_addc_u32 s47, s47, 0
	s_cmp_ge_u32 s71, s68
	s_mov_b32 s2, s71
	s_barrier
	s_cbranch_scc0 .LBB0_318
	s_branch .Lafter_318

.Lafter_318:
	s_cmp_gt_i32 s64, -1
	s_cbranch_scc0 .LBB0_321
	v_lshlrev_b32_e64 v0, v158, s64
	v_add_u32_e32 v130, s42, v0
	v_ashrrev_i32_e32 v131, 31, v130
	v_readlane_b32 s2, v255, 12
	v_lshlrev_b64 v[130:131], 19, v[130:131]
	v_readlane_b32 s3, v255, 13
	s_nop 1
	v_lshl_add_u64 v[156:157], s[2:3], 0, v[130:131]
	s_mov_b32 s2, 0
	s_cbranch_execnz .LBB0_303
	s_branch .LBB0_302

.LBB0_436:
	s_ashr_i32 s37, s36, 31
	v_cmp_lt_i64_e32 vcc, s[28:29], v[138:139]
	s_lshl_b64 s[22:23], s[36:37], 19
	v_readlane_b32 s28, v253, 45
	v_readlane_b32 s29, v253, 46
	s_add_u32 s30, s28, s22
	s_addc_u32 s31, s29, s23
	s_and_b64 s[22:23], vcc, exec
	s_cselect_b32 s22, s31, s21
	s_cselect_b32 s23, s30, s20
	s_ashr_i32 s43, s42, 31
	s_lshl_b64 s[28:29], s[42:43], 19
	v_readlane_b32 s46, v253, 31
	v_readlane_b32 s47, v253, 32
	s_add_u32 s46, s46, s28
	s_addc_u32 s47, s47, s29
	s_and_b64 s[28:29], vcc, exec
	s_cselect_b32 s37, s47, s3
	s_cselect_b32 s43, s46, s2
	s_add_u32 s20, s20, 0x40080
	s_addc_u32 s21, s21, 0
	s_add_u32 s65, s2, 0x100
	s_addc_u32 s66, s3, 0
	s_mov_b32 s67, -2
	s_waitcnt lgkmcnt(0)
	s_add_u32 s2, s20, 0xfffc0080
	s_addc_u32 s3, s21, -1
	s_add_i32 s68, 0, 0x10000
	v_add_u32_e32 v130, s68, v143
	ds_read_b128 v[168:171], v130
	ds_read_b128 v[172:175], v130 offset:1024
	ds_read_b128 v[176:179], v130 offset:2048
	ds_read_b128 v[180:183], v130 offset:3072
	s_cmp_eq_u32 s67, 12
	s_cselect_b32 s29, s22, s3
	s_cselect_b32 s28, s23, s2
	s_cselect_b32 s3, s37, s66
	s_cselect_b32 s2, s43, s65
	v_lshl_add_u64 v[130:131], s[20:21], 0, v[150:151]
	s_add_i32 m0, s99, 0xc000
	ds_read_b128 v[184:187], v157
	ds_read_b128 v[188:191], v157 offset:1024
	ds_read_b128 v[192:195], v157 offset:2048
	ds_read_b128 v[196:199], v157 offset:3072
	ds_read_b128 v[200:203], v157 offset:4096
	ds_read_b128 v[204:207], v157 offset:5120
	ds_read_b128 v[208:211], v157 offset:6144
	ds_read_b128 v[212:215], v157 offset:7168
	global_load_lds_dwordx4 v[130:131], off
	v_lshl_add_u64 v[130:131], s[20:21], 0, v[152:153]
	s_add_i32 m0, s99, 0xe000
	s_nop 0
	global_load_lds_dwordx4 v[130:131], off
	s_waitcnt lgkmcnt(8)
	s_barrier
	s_waitcnt lgkmcnt(0)
	v_mfma_f32_16x16x32_bf16 v[126:129], v[168:171], v[184:187], 0
	v_mfma_f32_16x16x32_bf16 v[114:117], v[176:179], v[184:187], 0
	v_mfma_f32_16x16x32_bf16 v[110:113], v[168:171], v[192:195], 0
	v_mfma_f32_16x16x32_bf16 v[98:101], v[176:179], v[192:195], 0
	v_mfma_f32_16x16x32_bf16 v[94:97], v[168:171], v[200:203], 0
	v_mfma_f32_16x16x32_bf16 v[82:85], v[176:179], v[200:203], 0
	v_mfma_f32_16x16x32_bf16 v[78:81], v[168:171], v[208:211], 0
	v_mfma_f32_16x16x32_bf16 v[66:69], v[176:179], v[208:211], 0
	v_mfma_f32_16x16x32_bf16 v[126:129], v[172:175], v[188:191], v[126:129]
	v_mfma_f32_16x16x32_bf16 v[114:117], v[180:183], v[188:191], v[114:117]
	v_mfma_f32_16x16x32_bf16 v[110:113], v[172:175], v[196:199], v[110:113]
	v_mfma_f32_16x16x32_bf16 v[98:101], v[180:183], v[196:199], v[98:101]
	v_mfma_f32_16x16x32_bf16 v[94:97], v[172:175], v[204:207], v[94:97]
	v_mfma_f32_16x16x32_bf16 v[82:85], v[180:183], v[204:207], v[82:85]
	v_mfma_f32_16x16x32_bf16 v[78:81], v[172:175], v[212:215], v[78:81]
	v_mfma_f32_16x16x32_bf16 v[66:69], v[180:183], v[212:215], v[66:69]
	s_barrier
	s_add_i32 s70, 0, 0x14000
	v_add_u32_e32 v130, s70, v143
	s_add_i32 s68, s68, s98
	ds_read_b128 v[216:219], v130
	ds_read_b128 v[220:223], v130 offset:1024
	ds_read_b128 v[224:227], v130 offset:2048
	ds_read_b128 v[228:231], v130 offset:3072
	v_lshl_add_u64 v[130:131], s[2:3], 0, v[0:1]
	s_mov_b32 m0, s68
	v_lshl_add_u64 v[132:133], s[2:3], 0, v[144:145]
	global_load_lds_dwordx4 v[130:131], off
	s_add_i32 m0, s68, 0x2000
	s_nop 0
	global_load_lds_dwordx4 v[132:133], off
	s_barrier
	s_waitcnt lgkmcnt(0)
	v_mfma_f32_16x16x32_bf16 v[122:125], v[216:219], v[184:187], 0
	v_mfma_f32_16x16x32_bf16 v[118:121], v[224:227], v[184:187], 0
	v_mfma_f32_16x16x32_bf16 v[106:109], v[216:219], v[192:195], 0
	v_mfma_f32_16x16x32_bf16 v[102:105], v[224:227], v[192:195], 0
	v_mfma_f32_16x16x32_bf16 v[90:93], v[216:219], v[200:203], 0
	v_mfma_f32_16x16x32_bf16 v[86:89], v[224:227], v[200:203], 0
	v_mfma_f32_16x16x32_bf16 v[74:77], v[216:219], v[208:211], 0
	v_mfma_f32_16x16x32_bf16 v[70:73], v[224:227], v[208:211], 0
	v_mfma_f32_16x16x32_bf16 v[122:125], v[220:223], v[188:191], v[122:125]
	v_mfma_f32_16x16x32_bf16 v[118:121], v[228:231], v[188:191], v[118:121]
	v_mfma_f32_16x16x32_bf16 v[106:109], v[220:223], v[196:199], v[106:109]
	v_mfma_f32_16x16x32_bf16 v[102:105], v[228:231], v[196:199], v[102:105]
	v_mfma_f32_16x16x32_bf16 v[90:93], v[220:223], v[204:207], v[90:93]
	v_mfma_f32_16x16x32_bf16 v[86:89], v[228:231], v[204:207], v[86:89]
	v_mfma_f32_16x16x32_bf16 v[74:77], v[220:223], v[212:215], v[74:77]
	v_mfma_f32_16x16x32_bf16 v[70:73], v[228:231], v[212:215], v[70:73]
	s_mov_b32 m0, s99
	v_lshl_add_u64 v[154:155], s[28:29], 0, v[148:149]
	s_barrier
	ds_read_b128 v[184:187], v157 offset:16384
	ds_read_b128 v[188:191], v157 offset:17408
	ds_read_b128 v[192:195], v157 offset:18432
	ds_read_b128 v[196:199], v157 offset:19456
	ds_read_b128 v[200:203], v157 offset:20480
	ds_read_b128 v[204:207], v157 offset:21504
	ds_read_b128 v[208:211], v157 offset:22528
	ds_read_b128 v[212:215], v157 offset:23552
	global_load_lds_dwordx4 v[154:155], off
	v_lshl_add_u64 v[158:159], s[28:29], 0, v[146:147]
	s_mov_b32 m0, s41
	s_nop 0
	global_load_lds_dwordx4 v[158:159], off
	s_barrier
	s_waitcnt lgkmcnt(0)
	v_mfma_f32_16x16x32_bf16 v[62:65], v[168:171], v[184:187], 0
	v_mfma_f32_16x16x32_bf16 v[50:53], v[176:179], v[184:187], 0
	v_mfma_f32_16x16x32_bf16 v[46:49], v[168:171], v[192:195], 0
	v_mfma_f32_16x16x32_bf16 v[34:37], v[176:179], v[192:195], 0
	v_mfma_f32_16x16x32_bf16 v[30:33], v[168:171], v[200:203], 0
	v_mfma_f32_16x16x32_bf16 v[18:21], v[176:179], v[200:203], 0
	v_mfma_f32_16x16x32_bf16 v[14:17], v[168:171], v[208:211], 0
	v_mfma_f32_16x16x32_bf16 v[6:9], v[176:179], v[208:211], 0
	v_mfma_f32_16x16x32_bf16 v[62:65], v[172:175], v[188:191], v[62:65]
	v_mfma_f32_16x16x32_bf16 v[50:53], v[180:183], v[188:191], v[50:53]
	v_mfma_f32_16x16x32_bf16 v[46:49], v[172:175], v[196:199], v[46:49]
	v_mfma_f32_16x16x32_bf16 v[34:37], v[180:183], v[196:199], v[34:37]
	v_mfma_f32_16x16x32_bf16 v[30:33], v[172:175], v[204:207], v[30:33]
	v_mfma_f32_16x16x32_bf16 v[18:21], v[180:183], v[204:207], v[18:21]
	v_mfma_f32_16x16x32_bf16 v[14:17], v[172:175], v[212:215], v[14:17]
	v_mfma_f32_16x16x32_bf16 v[6:9], v[180:183], v[212:215], v[6:9]
	s_barrier
	s_add_u32 s68, s2, 0x40000
	s_addc_u32 s69, s3, 0
	s_add_i32 s70, s70, s98
	v_lshl_add_u64 v[162:163], s[68:69], 0, v[0:1]
	s_mov_b32 m0, s70
	s_nop 0
	global_load_lds_dwordx4 v[162:163], off
	v_lshl_add_u64 v[162:163], s[68:69], 0, v[144:145]
	s_add_i32 m0, s70, 0x2000
	s_nop 0
	global_load_lds_dwordx4 v[162:163], off
	s_waitcnt vmcnt(6)
	s_barrier
	v_mfma_f32_16x16x32_bf16 v[58:61], v[216:219], v[184:187], 0
	v_mfma_f32_16x16x32_bf16 v[54:57], v[224:227], v[184:187], 0
	v_mfma_f32_16x16x32_bf16 v[42:45], v[216:219], v[192:195], 0
	v_mfma_f32_16x16x32_bf16 v[38:41], v[224:227], v[192:195], 0
	v_mfma_f32_16x16x32_bf16 v[26:29], v[216:219], v[200:203], 0
	v_mfma_f32_16x16x32_bf16 v[22:25], v[224:227], v[200:203], 0
	v_mfma_f32_16x16x32_bf16 v[10:13], v[216:219], v[208:211], 0
	v_mfma_f32_16x16x32_bf16 v[2:5], v[224:227], v[208:211], 0
	v_mfma_f32_16x16x32_bf16 v[58:61], v[220:223], v[188:191], v[58:61]
	v_mfma_f32_16x16x32_bf16 v[54:57], v[228:231], v[188:191], v[54:57]
	v_mfma_f32_16x16x32_bf16 v[42:45], v[220:223], v[196:199], v[42:45]
	v_mfma_f32_16x16x32_bf16 v[38:41], v[228:231], v[196:199], v[38:41]
	v_mfma_f32_16x16x32_bf16 v[26:29], v[220:223], v[204:207], v[26:29]
	v_mfma_f32_16x16x32_bf16 v[22:25], v[228:231], v[204:207], v[22:25]
	v_mfma_f32_16x16x32_bf16 v[10:13], v[220:223], v[212:215], v[10:13]
	v_mfma_f32_16x16x32_bf16 v[2:5], v[228:231], v[212:215], v[2:5]
	s_add_i32 s68, 0, 0x18000
	v_add_u32_e32 v162, s68, v143
	s_barrier
	ds_read_b128 v[168:171], v162
	ds_read_b128 v[172:175], v162 offset:1024
	ds_read_b128 v[176:179], v162 offset:2048
	ds_read_b128 v[180:183], v162 offset:3072
	s_add_u32 s28, s28, 0x40000
	s_addc_u32 s29, s29, 0
	s_mov_b32 m0, s96
	v_lshl_add_u64 v[162:163], s[28:29], 0, v[148:149]
	ds_read_b128 v[184:187], v157 offset:32768
	ds_read_b128 v[188:191], v157 offset:33792
	ds_read_b128 v[192:195], v157 offset:34816
	ds_read_b128 v[196:199], v157 offset:35840
	ds_read_b128 v[200:203], v157 offset:36864
	ds_read_b128 v[204:207], v157 offset:37888
	ds_read_b128 v[208:211], v157 offset:38912
	ds_read_b128 v[212:215], v157 offset:39936
	global_load_lds_dwordx4 v[162:163], off
	v_lshl_add_u64 v[162:163], s[28:29], 0, v[146:147]
	s_mov_b32 m0, s35
	s_nop 0
	global_load_lds_dwordx4 v[162:163], off
	s_waitcnt lgkmcnt(8)
	s_barrier
	s_waitcnt lgkmcnt(0)
	v_mfma_f32_16x16x32_bf16 v[126:129], v[168:171], v[184:187], v[126:129]
	v_mfma_f32_16x16x32_bf16 v[114:117], v[176:179], v[184:187], v[114:117]
	v_mfma_f32_16x16x32_bf16 v[110:113], v[168:171], v[192:195], v[110:113]
	v_mfma_f32_16x16x32_bf16 v[98:101], v[176:179], v[192:195], v[98:101]
	v_mfma_f32_16x16x32_bf16 v[94:97], v[168:171], v[200:203], v[94:97]
	v_mfma_f32_16x16x32_bf16 v[82:85], v[176:179], v[200:203], v[82:85]
	v_mfma_f32_16x16x32_bf16 v[78:81], v[168:171], v[208:211], v[78:81]
	v_mfma_f32_16x16x32_bf16 v[66:69], v[176:179], v[208:211], v[66:69]
	v_mfma_f32_16x16x32_bf16 v[126:129], v[172:175], v[188:191], v[126:129]
	v_mfma_f32_16x16x32_bf16 v[114:117], v[180:183], v[188:191], v[114:117]
	v_mfma_f32_16x16x32_bf16 v[110:113], v[172:175], v[196:199], v[110:113]
	v_mfma_f32_16x16x32_bf16 v[98:101], v[180:183], v[196:199], v[98:101]
	v_mfma_f32_16x16x32_bf16 v[94:97], v[172:175], v[204:207], v[94:97]
	v_mfma_f32_16x16x32_bf16 v[82:85], v[180:183], v[204:207], v[82:85]
	v_mfma_f32_16x16x32_bf16 v[78:81], v[172:175], v[212:215], v[78:81]
	v_mfma_f32_16x16x32_bf16 v[66:69], v[180:183], v[212:215], v[66:69]
	s_barrier
	s_add_i32 s28, 0, 0x1c000
	s_add_i32 s29, s68, s98
	v_add_u32_e32 v162, s28, v143
	v_lshl_add_u64 v[130:131], v[130:131], 0, s[26:27]
	s_mov_b32 m0, s29
	ds_read_b128 v[216:219], v162
	ds_read_b128 v[220:223], v162 offset:1024
	ds_read_b128 v[224:227], v162 offset:2048
	ds_read_b128 v[228:231], v162 offset:3072
	global_load_lds_dwordx4 v[130:131], off
	v_lshl_add_u64 v[130:131], v[132:133], 0, s[26:27]
	s_add_i32 m0, s29, 0x2000
	s_nop 0
	global_load_lds_dwordx4 v[130:131], off
	s_barrier
	s_waitcnt lgkmcnt(0)
	v_mfma_f32_16x16x32_bf16 v[122:125], v[216:219], v[184:187], v[122:125]
	v_mfma_f32_16x16x32_bf16 v[118:121], v[224:227], v[184:187], v[118:121]
	v_mfma_f32_16x16x32_bf16 v[106:109], v[216:219], v[192:195], v[106:109]
	v_mfma_f32_16x16x32_bf16 v[102:105], v[224:227], v[192:195], v[102:105]
	v_mfma_f32_16x16x32_bf16 v[90:93], v[216:219], v[200:203], v[90:93]
	v_mfma_f32_16x16x32_bf16 v[86:89], v[224:227], v[200:203], v[86:89]
	v_mfma_f32_16x16x32_bf16 v[74:77], v[216:219], v[208:211], v[74:77]
	v_mfma_f32_16x16x32_bf16 v[70:73], v[224:227], v[208:211], v[70:73]
	v_mfma_f32_16x16x32_bf16 v[122:125], v[220:223], v[188:191], v[122:125]
	v_mfma_f32_16x16x32_bf16 v[118:121], v[228:231], v[188:191], v[118:121]
	v_mfma_f32_16x16x32_bf16 v[106:109], v[220:223], v[196:199], v[106:109]
	v_mfma_f32_16x16x32_bf16 v[102:105], v[228:231], v[196:199], v[102:105]
	v_mfma_f32_16x16x32_bf16 v[90:93], v[220:223], v[204:207], v[90:93]
	v_mfma_f32_16x16x32_bf16 v[86:89], v[228:231], v[204:207], v[86:89]
	v_mfma_f32_16x16x32_bf16 v[74:77], v[220:223], v[212:215], v[74:77]
	v_mfma_f32_16x16x32_bf16 v[70:73], v[228:231], v[212:215], v[70:73]
	s_mov_b32 m0, s33
	v_lshl_add_u64 v[130:131], v[154:155], 0, s[26:27]
	s_barrier
	ds_read_b128 v[184:187], v157 offset:49152
	ds_read_b128 v[188:191], v157 offset:50176
	ds_read_b128 v[192:195], v157 offset:51200
	ds_read_b128 v[196:199], v157 offset:52224
	ds_read_b128 v[200:203], v157 offset:53248
	ds_read_b128 v[204:207], v157 offset:54272
	ds_read_b128 v[208:211], v157 offset:55296
	ds_read_b128 v[212:215], v157 offset:56320
	global_load_lds_dwordx4 v[130:131], off
	v_lshl_add_u64 v[130:131], v[158:159], 0, s[26:27]
	s_mov_b32 m0, s44
	s_nop 0
	global_load_lds_dwordx4 v[130:131], off
	s_barrier
	s_waitcnt lgkmcnt(0)
	v_mfma_f32_16x16x32_bf16 v[62:65], v[168:171], v[184:187], v[62:65]
	v_mfma_f32_16x16x32_bf16 v[50:53], v[176:179], v[184:187], v[50:53]
	v_mfma_f32_16x16x32_bf16 v[46:49], v[168:171], v[192:195], v[46:49]
	v_mfma_f32_16x16x32_bf16 v[34:37], v[176:179], v[192:195], v[34:37]
	v_mfma_f32_16x16x32_bf16 v[30:33], v[168:171], v[200:203], v[30:33]
	v_mfma_f32_16x16x32_bf16 v[18:21], v[176:179], v[200:203], v[18:21]
	v_mfma_f32_16x16x32_bf16 v[14:17], v[168:171], v[208:211], v[14:17]
	v_mfma_f32_16x16x32_bf16 v[6:9], v[176:179], v[208:211], v[6:9]
	v_mfma_f32_16x16x32_bf16 v[62:65], v[172:175], v[188:191], v[62:65]
	v_mfma_f32_16x16x32_bf16 v[50:53], v[180:183], v[188:191], v[50:53]
	v_mfma_f32_16x16x32_bf16 v[46:49], v[172:175], v[196:199], v[46:49]
	v_mfma_f32_16x16x32_bf16 v[34:37], v[180:183], v[196:199], v[34:37]
	v_mfma_f32_16x16x32_bf16 v[30:33], v[172:175], v[204:207], v[30:33]
	v_mfma_f32_16x16x32_bf16 v[18:21], v[180:183], v[204:207], v[18:21]
	v_mfma_f32_16x16x32_bf16 v[14:17], v[172:175], v[212:215], v[14:17]
	v_mfma_f32_16x16x32_bf16 v[6:9], v[180:183], v[212:215], v[6:9]
	s_barrier
	s_add_u32 s2, s2, 0x40080
	s_addc_u32 s3, s3, 0
	s_add_i32 s28, s28, s98
	v_lshl_add_u64 v[130:131], s[2:3], 0, v[0:1]
	s_mov_b32 m0, s28
	s_nop 0
	global_load_lds_dwordx4 v[130:131], off
	v_lshl_add_u64 v[130:131], s[2:3], 0, v[144:145]
	s_add_i32 m0, s28, 0x2000
	s_nop 0
	global_load_lds_dwordx4 v[130:131], off
	s_waitcnt vmcnt(6)
	s_barrier
	v_mfma_f32_16x16x32_bf16 v[58:61], v[216:219], v[184:187], v[58:61]
	v_mfma_f32_16x16x32_bf16 v[54:57], v[224:227], v[184:187], v[54:57]
	v_mfma_f32_16x16x32_bf16 v[42:45], v[216:219], v[192:195], v[42:45]
	v_mfma_f32_16x16x32_bf16 v[38:41], v[224:227], v[192:195], v[38:41]
	v_mfma_f32_16x16x32_bf16 v[26:29], v[216:219], v[200:203], v[26:29]
	v_mfma_f32_16x16x32_bf16 v[22:25], v[224:227], v[200:203], v[22:25]
	v_mfma_f32_16x16x32_bf16 v[10:13], v[216:219], v[208:211], v[10:13]
	v_mfma_f32_16x16x32_bf16 v[2:5], v[224:227], v[208:211], v[2:5]
	v_mfma_f32_16x16x32_bf16 v[58:61], v[220:223], v[188:191], v[58:61]
	v_mfma_f32_16x16x32_bf16 v[54:57], v[228:231], v[188:191], v[54:57]
	v_mfma_f32_16x16x32_bf16 v[42:45], v[220:223], v[196:199], v[42:45]
	v_mfma_f32_16x16x32_bf16 v[38:41], v[228:231], v[196:199], v[38:41]
	v_mfma_f32_16x16x32_bf16 v[26:29], v[220:223], v[204:207], v[26:29]
	v_mfma_f32_16x16x32_bf16 v[22:25], v[228:231], v[204:207], v[22:25]
	v_mfma_f32_16x16x32_bf16 v[10:13], v[220:223], v[212:215], v[10:13]
	v_mfma_f32_16x16x32_bf16 v[2:5], v[228:231], v[212:215], v[2:5]
	s_add_i32 s67, s67, 2
	s_add_u32 s20, s20, 0x100
	s_addc_u32 s21, s21, 0
	s_add_u32 s65, s65, 0x100
	s_addc_u32 s66, s66, 0
	s_cmp_gt_u32 s67, 13
	s_barrier
	s_cbranch_scc0 .LBB0_437
	s_branch .Lafter_437

.Lafter_437:
	s_andn2_b64 vcc, exec, s[0:1]
	s_cbranch_vccnz .LBB0_429
	v_pk_mul_f32 v[162:163], v[126:127], s[34:35] op_sel_hi:[1,0]
	v_pk_mul_f32 v[122:123], v[122:123], v[126:127]
	v_pk_mul_f32 v[126:127], v[128:129], s[34:35] op_sel_hi:[1,0]
	v_exp_f32_e32 v162, v162
	v_exp_f32_e32 v163, v163
	v_exp_f32_e32 v126, v126
	v_exp_f32_e32 v127, v127
	v_pk_mul_f32 v[124:125], v[124:125], v[128:129]
	v_pk_add_f32 v[162:163], v[162:163], 1.0 op_sel_hi:[1,0]
	v_pk_mul_f32 v[106:107], v[106:107], v[110:111]
	v_pk_add_f32 v[126:127], v[126:127], 1.0 op_sel_hi:[1,0]
	v_rcp_f32_e32 v162, v162
	v_rcp_f32_e32 v163, v163
	v_rcp_f32_e32 v126, v126
	v_rcp_f32_e32 v127, v127
	v_lshl_or_b32 v130, s40, 7, v156
	v_pk_mul_f32 v[122:123], v[122:123], v[162:163]
	v_pk_mul_f32 v[120:121], v[120:121], v[116:117]
	v_pk_mul_f32 v[124:125], v[124:125], v[126:127]
	v_cvt_pk_bf16_f32 v122, v122, v123
	v_lshl_add_u32 v158, s64, 8, v141
	v_cvt_pk_bf16_f32 v123, v124, v125
	v_pk_mul_f32 v[124:125], v[114:115], s[34:35] op_sel_hi:[1,0]
	v_pk_mul_f32 v[114:115], v[118:119], v[114:115]
	v_exp_f32_e32 v124, v124
	v_exp_f32_e32 v125, v125
	v_pk_mul_f32 v[118:119], v[110:111], s[34:35] op_sel_hi:[1,0]
	v_pk_mul_f32 v[110:111], v[112:113], s[34:35] op_sel_hi:[1,0]
	v_exp_f32_e32 v118, v118
	v_pk_add_f32 v[124:125], v[124:125], 1.0 op_sel_hi:[1,0]
	v_exp_f32_e32 v119, v119
	v_rcp_f32_e32 v124, v124
	v_rcp_f32_e32 v125, v125
	v_exp_f32_e32 v110, v110
	v_exp_f32_e32 v111, v111
	v_pk_add_f32 v[118:119], v[118:119], 1.0 op_sel_hi:[1,0]
	v_pk_mul_f32 v[114:115], v[114:115], v[124:125]
	v_rcp_f32_e32 v118, v118
	v_cvt_pk_bf16_f32 v124, v114, v115
	v_pk_mul_f32 v[114:115], v[116:117], s[34:35] op_sel_hi:[1,0]
	v_pk_add_f32 v[110:111], v[110:111], 1.0 op_sel_hi:[1,0]
	v_exp_f32_e32 v114, v114
	v_exp_f32_e32 v115, v115
	v_rcp_f32_e32 v119, v119
	v_rcp_f32_e32 v110, v110
	v_rcp_f32_e32 v111, v111
	v_pk_add_f32 v[114:115], v[114:115], 1.0 op_sel_hi:[1,0]
	v_ashrrev_i32_e32 v131, 31, v130
	v_rcp_f32_e32 v114, v114
	v_rcp_f32_e32 v115, v115
	v_mov_b64_e32 v[154:155], s[62:63]
	s_movk_i32 s20, 0x1600
	v_mad_i64_i32 v[132:133], s[2:3], v158, s20, v[154:155]
	v_pk_mul_f32 v[114:115], v[120:121], v[114:115]
	v_pk_mul_f32 v[108:109], v[108:109], v[112:113]
	v_cvt_pk_bf16_f32 v125, v114, v115
	v_lshlrev_b64 v[114:115], 1, v[130:131]
	v_lshl_add_u64 v[116:117], v[132:133], 0, v[114:115]
	v_pk_mul_f32 v[106:107], v[106:107], v[118:119]
	v_pk_mul_f32 v[108:109], v[108:109], v[110:111]
	global_store_dwordx4 v[116:117], v[122:125], off
	v_cvt_pk_bf16_f32 v106, v106, v107
	v_cvt_pk_bf16_f32 v107, v108, v109
	v_pk_mul_f32 v[108:109], v[98:99], s[34:35] op_sel_hi:[1,0]
	v_pk_mul_f32 v[98:99], v[102:103], v[98:99]
	v_exp_f32_e32 v108, v108
	v_exp_f32_e32 v109, v109
	v_pk_mul_f32 v[104:105], v[104:105], v[100:101]
	v_pk_mul_f32 v[90:91], v[90:91], v[94:95]
	v_or_b32_e32 v116, 16, v158
	v_pk_add_f32 v[108:109], v[108:109], 1.0 op_sel_hi:[1,0]
	v_mad_i64_i32 v[116:117], s[2:3], v116, s20, v[154:155]
	v_rcp_f32_e32 v108, v108
	v_rcp_f32_e32 v109, v109
	v_pk_mul_f32 v[92:93], v[92:93], v[96:97]
	v_pk_mul_f32 v[88:89], v[88:89], v[84:85]
	v_pk_mul_f32 v[74:75], v[74:75], v[78:79]
	v_pk_mul_f32 v[98:99], v[98:99], v[108:109]
	v_pk_mul_f32 v[76:77], v[76:77], v[80:81]
	v_cvt_pk_bf16_f32 v108, v98, v99
	v_pk_mul_f32 v[98:99], v[100:101], s[34:35] op_sel_hi:[1,0]
	v_pk_mul_f32 v[100:101], v[94:95], s[34:35] op_sel_hi:[1,0]
	v_exp_f32_e32 v98, v98
	v_exp_f32_e32 v99, v99
	v_pk_mul_f32 v[94:95], v[96:97], s[34:35] op_sel_hi:[1,0]
	v_exp_f32_e32 v100, v100
	v_exp_f32_e32 v101, v101
	v_exp_f32_e32 v94, v94
	v_exp_f32_e32 v95, v95
	v_pk_add_f32 v[98:99], v[98:99], 1.0 op_sel_hi:[1,0]
	v_pk_add_f32 v[100:101], v[100:101], 1.0 op_sel_hi:[1,0]
	v_rcp_f32_e32 v98, v98
	v_rcp_f32_e32 v99, v99
	v_pk_add_f32 v[94:95], v[94:95], 1.0 op_sel_hi:[1,0]
	v_rcp_f32_e32 v100, v100
	v_rcp_f32_e32 v101, v101
	v_rcp_f32_e32 v94, v94
	v_rcp_f32_e32 v95, v95
	v_pk_mul_f32 v[98:99], v[104:105], v[98:99]
	v_pk_mul_f32 v[90:91], v[90:91], v[100:101]
	v_cvt_pk_bf16_f32 v109, v98, v99
	v_lshl_add_u64 v[98:99], v[116:117], 0, v[114:115]
	v_pk_mul_f32 v[92:93], v[92:93], v[94:95]
	global_store_dwordx4 v[98:99], v[106:109], off
	v_cvt_pk_bf16_f32 v90, v90, v91
	v_cvt_pk_bf16_f32 v91, v92, v93
	v_pk_mul_f32 v[92:93], v[82:83], s[34:35] op_sel_hi:[1,0]
	v_pk_mul_f32 v[82:83], v[86:87], v[82:83]
	v_exp_f32_e32 v92, v92
	v_exp_f32_e32 v93, v93
	v_or_b32_e32 v98, 32, v158
	v_mad_i64_i32 v[98:99], s[2:3], v98, s20, v[154:155]
	v_pk_add_f32 v[92:93], v[92:93], 1.0 op_sel_hi:[1,0]
	v_pk_mul_f32 v[72:73], v[72:73], v[68:69]
	v_rcp_f32_e32 v92, v92
	v_rcp_f32_e32 v93, v93
	v_pk_mul_f32 v[58:59], v[58:59], v[62:63]
	v_pk_mul_f32 v[60:61], v[60:61], v[64:65]
	v_pk_mul_f32 v[56:57], v[56:57], v[52:53]
	v_pk_mul_f32 v[82:83], v[82:83], v[92:93]
	v_pk_mul_f32 v[42:43], v[42:43], v[46:47]
	v_cvt_pk_bf16_f32 v92, v82, v83
	v_pk_mul_f32 v[82:83], v[84:85], s[34:35] op_sel_hi:[1,0]
	v_pk_mul_f32 v[84:85], v[78:79], s[34:35] op_sel_hi:[1,0]
	v_exp_f32_e32 v82, v82
	v_exp_f32_e32 v83, v83
	v_pk_mul_f32 v[78:79], v[80:81], s[34:35] op_sel_hi:[1,0]
	v_exp_f32_e32 v84, v84
	v_exp_f32_e32 v85, v85
	v_exp_f32_e32 v78, v78
	v_exp_f32_e32 v79, v79
	v_pk_add_f32 v[82:83], v[82:83], 1.0 op_sel_hi:[1,0]
	v_pk_add_f32 v[84:85], v[84:85], 1.0 op_sel_hi:[1,0]
	v_rcp_f32_e32 v82, v82
	v_rcp_f32_e32 v83, v83
	v_pk_add_f32 v[78:79], v[78:79], 1.0 op_sel_hi:[1,0]
	v_rcp_f32_e32 v84, v84
	v_rcp_f32_e32 v85, v85
	v_rcp_f32_e32 v78, v78
	v_rcp_f32_e32 v79, v79
	v_pk_mul_f32 v[82:83], v[88:89], v[82:83]
	v_pk_mul_f32 v[74:75], v[74:75], v[84:85]
	v_cvt_pk_bf16_f32 v93, v82, v83
	v_lshl_add_u64 v[82:83], v[98:99], 0, v[114:115]
	v_pk_mul_f32 v[76:77], v[76:77], v[78:79]
	global_store_dwordx4 v[82:83], v[90:93], off
	v_cvt_pk_bf16_f32 v74, v74, v75
	v_cvt_pk_bf16_f32 v75, v76, v77
	v_pk_mul_f32 v[76:77], v[66:67], s[34:35] op_sel_hi:[1,0]
	v_pk_mul_f32 v[66:67], v[70:71], v[66:67]
	v_exp_f32_e32 v76, v76
	v_exp_f32_e32 v77, v77
	v_or_b32_e32 v82, 48, v158
	v_mad_i64_i32 v[82:83], s[2:3], v82, s20, v[154:155]
	v_pk_add_f32 v[76:77], v[76:77], 1.0 op_sel_hi:[1,0]
	v_pk_mul_f32 v[44:45], v[44:45], v[48:49]
	v_rcp_f32_e32 v76, v76
	v_rcp_f32_e32 v77, v77
	v_pk_mul_f32 v[40:41], v[40:41], v[36:37]
	v_pk_mul_f32 v[26:27], v[26:27], v[30:31]
	v_pk_mul_f32 v[28:29], v[28:29], v[32:33]
	v_pk_mul_f32 v[66:67], v[66:67], v[76:77]
	v_pk_mul_f32 v[24:25], v[24:25], v[20:21]
	v_cvt_pk_bf16_f32 v76, v66, v67
	v_pk_mul_f32 v[66:67], v[68:69], s[34:35] op_sel_hi:[1,0]
	v_pk_mul_f32 v[68:69], v[62:63], s[34:35] op_sel_hi:[1,0]
	v_exp_f32_e32 v66, v66
	v_exp_f32_e32 v67, v67
	v_pk_mul_f32 v[62:63], v[64:65], s[34:35] op_sel_hi:[1,0]
	v_exp_f32_e32 v68, v68
	v_exp_f32_e32 v69, v69
	v_exp_f32_e32 v62, v62
	v_exp_f32_e32 v63, v63
	v_pk_add_f32 v[66:67], v[66:67], 1.0 op_sel_hi:[1,0]
	v_pk_add_f32 v[68:69], v[68:69], 1.0 op_sel_hi:[1,0]
	v_rcp_f32_e32 v66, v66
	v_rcp_f32_e32 v67, v67
	v_pk_add_f32 v[62:63], v[62:63], 1.0 op_sel_hi:[1,0]
	v_rcp_f32_e32 v68, v68
	v_rcp_f32_e32 v69, v69
	v_rcp_f32_e32 v62, v62
	v_rcp_f32_e32 v63, v63
	v_pk_mul_f32 v[66:67], v[72:73], v[66:67]
	v_pk_mul_f32 v[58:59], v[58:59], v[68:69]
	v_cvt_pk_bf16_f32 v77, v66, v67
	v_lshl_add_u64 v[66:67], v[82:83], 0, v[114:115]
	v_pk_mul_f32 v[60:61], v[60:61], v[62:63]
	global_store_dwordx4 v[66:67], v[74:77], off
	v_cvt_pk_bf16_f32 v58, v58, v59
	v_cvt_pk_bf16_f32 v59, v60, v61
	v_pk_mul_f32 v[60:61], v[50:51], s[34:35] op_sel_hi:[1,0]
	v_pk_mul_f32 v[50:51], v[54:55], v[50:51]
	v_exp_f32_e32 v60, v60
	v_exp_f32_e32 v61, v61
	v_add_u32_e32 v66, 0x80, v158
	v_mad_i64_i32 v[66:67], s[2:3], v66, s20, v[154:155]
	v_pk_add_f32 v[60:61], v[60:61], 1.0 op_sel_hi:[1,0]
	v_pk_mul_f32 v[10:11], v[10:11], v[14:15]
	v_rcp_f32_e32 v60, v60
	v_rcp_f32_e32 v61, v61
	v_pk_mul_f32 v[12:13], v[12:13], v[16:17]
	v_pk_mul_f32 v[2:3], v[2:3], v[6:7]
	v_pk_mul_f32 v[4:5], v[4:5], v[8:9]
	v_pk_mul_f32 v[50:51], v[50:51], v[60:61]
	s_nop 0
	v_cvt_pk_bf16_f32 v60, v50, v51
	v_pk_mul_f32 v[50:51], v[52:53], s[34:35] op_sel_hi:[1,0]
	v_pk_mul_f32 v[52:53], v[46:47], s[34:35] op_sel_hi:[1,0]
	v_exp_f32_e32 v50, v50
	v_exp_f32_e32 v51, v51
	v_pk_mul_f32 v[46:47], v[48:49], s[34:35] op_sel_hi:[1,0]
	v_exp_f32_e32 v52, v52
	v_exp_f32_e32 v53, v53
	v_exp_f32_e32 v46, v46
	v_exp_f32_e32 v47, v47
	v_pk_add_f32 v[50:51], v[50:51], 1.0 op_sel_hi:[1,0]
	v_pk_add_f32 v[52:53], v[52:53], 1.0 op_sel_hi:[1,0]
	v_rcp_f32_e32 v50, v50
	v_rcp_f32_e32 v51, v51
	v_pk_add_f32 v[46:47], v[46:47], 1.0 op_sel_hi:[1,0]
	v_rcp_f32_e32 v52, v52
	v_rcp_f32_e32 v53, v53
	v_rcp_f32_e32 v46, v46
	v_rcp_f32_e32 v47, v47
	v_pk_mul_f32 v[50:51], v[56:57], v[50:51]
	v_pk_mul_f32 v[42:43], v[42:43], v[52:53]
	v_cvt_pk_bf16_f32 v61, v50, v51
	v_lshl_add_u64 v[50:51], v[66:67], 0, v[114:115]
	v_pk_mul_f32 v[44:45], v[44:45], v[46:47]
	global_store_dwordx4 v[50:51], v[58:61], off
	v_cvt_pk_bf16_f32 v42, v42, v43
	v_cvt_pk_bf16_f32 v43, v44, v45
	v_pk_mul_f32 v[44:45], v[34:35], s[34:35] op_sel_hi:[1,0]
	v_pk_mul_f32 v[34:35], v[38:39], v[34:35]
	v_exp_f32_e32 v44, v44
	v_exp_f32_e32 v45, v45
	v_add_u32_e32 v50, 0x90, v158
	v_mad_i64_i32 v[50:51], s[2:3], v50, s20, v[154:155]
	v_pk_add_f32 v[44:45], v[44:45], 1.0 op_sel_hi:[1,0]
	s_nop 0
	v_rcp_f32_e32 v44, v44
	v_rcp_f32_e32 v45, v45
	s_nop 0
	v_pk_mul_f32 v[34:35], v[34:35], v[44:45]
	s_nop 0
	v_cvt_pk_bf16_f32 v44, v34, v35
	v_pk_mul_f32 v[34:35], v[36:37], s[34:35] op_sel_hi:[1,0]
	v_pk_mul_f32 v[36:37], v[30:31], s[34:35] op_sel_hi:[1,0]
	v_exp_f32_e32 v34, v34
	v_exp_f32_e32 v35, v35
	v_pk_mul_f32 v[30:31], v[32:33], s[34:35] op_sel_hi:[1,0]
	v_exp_f32_e32 v36, v36
	v_exp_f32_e32 v37, v37
	v_exp_f32_e32 v30, v30
	v_exp_f32_e32 v31, v31
	v_pk_add_f32 v[34:35], v[34:35], 1.0 op_sel_hi:[1,0]
	v_pk_add_f32 v[36:37], v[36:37], 1.0 op_sel_hi:[1,0]
	v_rcp_f32_e32 v34, v34
	v_rcp_f32_e32 v35, v35
	v_pk_add_f32 v[30:31], v[30:31], 1.0 op_sel_hi:[1,0]
	v_rcp_f32_e32 v36, v36
	v_rcp_f32_e32 v37, v37
	v_rcp_f32_e32 v30, v30
	v_rcp_f32_e32 v31, v31
	v_pk_mul_f32 v[34:35], v[40:41], v[34:35]
	v_pk_mul_f32 v[26:27], v[26:27], v[36:37]
	v_cvt_pk_bf16_f32 v45, v34, v35
	v_lshl_add_u64 v[34:35], v[50:51], 0, v[114:115]
	v_pk_mul_f32 v[28:29], v[28:29], v[30:31]
	global_store_dwordx4 v[34:35], v[42:45], off
	v_cvt_pk_bf16_f32 v26, v26, v27
	v_cvt_pk_bf16_f32 v27, v28, v29
	v_pk_mul_f32 v[28:29], v[18:19], s[34:35] op_sel_hi:[1,0]
	v_pk_mul_f32 v[18:19], v[22:23], v[18:19]
	v_exp_f32_e32 v28, v28
	v_exp_f32_e32 v29, v29
	v_add_u32_e32 v34, 0xa0, v158
	v_mad_i64_i32 v[34:35], s[2:3], v34, s20, v[154:155]
	v_pk_add_f32 v[28:29], v[28:29], 1.0 op_sel_hi:[1,0]
	s_nop 0
	v_rcp_f32_e32 v28, v28
	v_rcp_f32_e32 v29, v29
	s_nop 0
	v_pk_mul_f32 v[18:19], v[18:19], v[28:29]
	s_nop 0
	v_cvt_pk_bf16_f32 v28, v18, v19
	v_pk_mul_f32 v[18:19], v[20:21], s[34:35] op_sel_hi:[1,0]
	v_pk_mul_f32 v[20:21], v[14:15], s[34:35] op_sel_hi:[1,0]
	v_exp_f32_e32 v18, v18
	v_exp_f32_e32 v19, v19
	v_pk_mul_f32 v[14:15], v[16:17], s[34:35] op_sel_hi:[1,0]
	v_exp_f32_e32 v20, v20
	v_exp_f32_e32 v21, v21
	v_exp_f32_e32 v14, v14
	v_exp_f32_e32 v15, v15
	v_pk_add_f32 v[18:19], v[18:19], 1.0 op_sel_hi:[1,0]
	v_pk_add_f32 v[20:21], v[20:21], 1.0 op_sel_hi:[1,0]
	v_rcp_f32_e32 v18, v18
	v_rcp_f32_e32 v19, v19
	v_pk_add_f32 v[14:15], v[14:15], 1.0 op_sel_hi:[1,0]
	v_rcp_f32_e32 v20, v20
	v_rcp_f32_e32 v21, v21
	v_rcp_f32_e32 v14, v14
	v_rcp_f32_e32 v15, v15
	v_pk_mul_f32 v[18:19], v[24:25], v[18:19]
	v_pk_mul_f32 v[10:11], v[10:11], v[20:21]
	v_cvt_pk_bf16_f32 v29, v18, v19
	v_lshl_add_u64 v[18:19], v[34:35], 0, v[114:115]
	v_pk_mul_f32 v[12:13], v[12:13], v[14:15]
	global_store_dwordx4 v[18:19], v[26:29], off
	v_cvt_pk_bf16_f32 v10, v10, v11
	v_cvt_pk_bf16_f32 v11, v12, v13
	v_pk_mul_f32 v[12:13], v[6:7], s[34:35] op_sel_hi:[1,0]
	v_add_u32_e32 v18, 0xb0, v158
	v_exp_f32_e32 v12, v12
	v_exp_f32_e32 v13, v13
	v_mad_i64_i32 v[18:19], s[2:3], v18, s20, v[154:155]
	v_pk_add_f32 v[12:13], v[12:13], 1.0 op_sel_hi:[1,0]
	s_nop 0
	v_rcp_f32_e32 v12, v12
	v_rcp_f32_e32 v13, v13
	s_nop 0
	v_pk_mul_f32 v[2:3], v[2:3], v[12:13]
	s_nop 0
	v_cvt_pk_bf16_f32 v12, v2, v3
	v_pk_mul_f32 v[2:3], v[8:9], s[34:35] op_sel_hi:[1,0]
	s_nop 0
	v_exp_f32_e32 v2, v2
	v_exp_f32_e32 v3, v3
	s_nop 0
	v_pk_add_f32 v[2:3], v[2:3], 1.0 op_sel_hi:[1,0]
	s_nop 0
	v_rcp_f32_e32 v2, v2
	v_rcp_f32_e32 v3, v3
	s_nop 0
	v_pk_mul_f32 v[2:3], v[4:5], v[2:3]
	s_nop 0
	v_cvt_pk_bf16_f32 v13, v2, v3
	v_lshl_add_u64 v[2:3], v[18:19], 0, v[114:115]
	global_store_dwordx4 v[2:3], v[10:13], off
	s_branch .LBB0_429
